# counted lgkmcnt inside the A-read MFMA segments: each MFMA pair waits only for its own A fragment
# speedup vs baseline: 1.0027x; 1.0020x over previous
.LBB0_415:
	v_writelane_b32 v250, s5, 0
	v_writelane_b32 v250, s23, 1
	v_writelane_b32 v250, s26, 2
	v_writelane_b32 v250, s27, 3
	v_writelane_b32 v250, s28, 4
	v_writelane_b32 v250, s29, 5
	v_writelane_b32 v250, s42, 6
	v_writelane_b32 v250, s43, 7
	v_writelane_b32 v250, s44, 8
	v_writelane_b32 v250, s45, 9
	v_writelane_b32 v250, s46, 10
	v_writelane_b32 v250, s47, 11
	v_writelane_b32 v250, s48, 12
	v_writelane_b32 v250, s49, 13
	v_writelane_b32 v250, s50, 14
	v_writelane_b32 v250, s51, 15
	v_writelane_b32 v250, s53, 16
	v_writelane_b32 v250, s54, 17
	v_writelane_b32 v250, s55, 18
	v_writelane_b32 v250, s56, 19
	v_writelane_b32 v250, s57, 20
	v_writelane_b32 v250, s58, 21
	v_writelane_b32 v250, s59, 22
	v_writelane_b32 v250, s60, 23
	v_writelane_b32 v250, s61, 24
	v_writelane_b32 v250, s63, 25
	v_writelane_b32 v250, s64, 26
	v_writelane_b32 v250, s65, 27
	s_add_i32 s53, s90, 0x80
	s_add_i32 s54, s52, -4
	s_add_i32 s55, s52, -3
	s_mov_b32 s56, s48
	s_add_i32 s57, s56, 0x2000
	s_add_i32 s58, s56, 0x4000
	s_add_i32 s59, s56, 0x6000
	s_add_i32 s60, s56, 0x8000
	s_add_i32 s61, s56, 0xa000
	v_readfirstlane_b32 s42, v6
	v_readfirstlane_b32 s43, v7
	v_readfirstlane_b32 s28, v4
	v_readfirstlane_b32 s29, v5
	v_readfirstlane_b32 s26, v146
	v_readfirstlane_b32 s5, v147
	v_readfirstlane_b32 s27, v148
	v_readfirstlane_b32 s23, v149
	s_add_u32 s28, s28, 0x100
	s_addc_u32 s29, s29, 0
	s_mov_b32 s63, -2
	v_mov_b32_e32 v4, 0
	s_add_u32 s44, s42, 0x100
	s_addc_u32 s45, s43, 0
	s_cmp_eq_u32 s63, s54
	s_cselect_b32 s50, s26, s44
	s_cselect_b32 s51, s5, s45
	s_cselect_b32 s48, s27, s28
	s_cselect_b32 s49, s23, s29
	s_add_i32 s64, 0, 0x10000
	s_add_u32 s46, s42, 0x80
	s_addc_u32 s47, s43, 0
	s_add_u32 s42, s42, s53
	s_addc_u32 s43, s43, 0
	s_mov_b32 m0, s60
	s_nop 0
	global_load_lds_dwordx4 v0, s[46:47]
	s_mov_b32 m0, s61
	s_nop 0
	global_load_lds_dwordx4 v142, s[46:47]
	v_add_u32_e32 v187, s64, v3
	s_add_i32 s65, 0, 0x14000
	ds_read_b128 v[164:167], v187
	ds_read_b128 v[168:171], v187 offset:1024
	ds_read_b128 v[188:191], v187 offset:2048
	ds_read_b128 v[192:195], v187 offset:3072
	v_add_u32_e32 v187, s65, v3
	ds_read_b128 v[196:199], v187
	ds_read_b128 v[200:203], v187 offset:1024
	ds_read_b128 v[204:207], v187 offset:2048
	ds_read_b128 v[208:211], v187 offset:3072
	s_add_i32 m0, s56, 0xc000
	s_nop 0
	global_load_lds_dwordx4 v0, s[42:43]
	s_add_i32 m0, s56, 0xe000
	s_nop 0
	global_load_lds_dwordx4 v142, s[42:43]
	ds_read_b128 v[212:215], v160
	ds_read_b128 v[216:219], v160 offset:1024
	ds_read_b128 v[220:223], v160 offset:2048
	ds_read_b128 v[224:227], v160 offset:3072
	ds_read_b128 v[228:231], v160 offset:4096
	ds_read_b128 v[232:235], v160 offset:5120
	ds_read_b128 v[236:239], v160 offset:6144
	ds_read_b128 v[240:243], v160 offset:7168
	s_waitcnt vmcnt(8)
	s_waitcnt lgkmcnt(8)
	s_barrier
	s_setprio 1
	s_waitcnt lgkmcnt(7)
	v_mfma_f32_16x16x32_bf16 v[128:131], v[164:167], v[212:215], 0
	v_mfma_f32_16x16x32_bf16 v[124:127], v[188:191], v[212:215], 0
	s_waitcnt lgkmcnt(5)
	v_mfma_f32_16x16x32_bf16 v[112:115], v[164:167], v[220:223], 0
	v_mfma_f32_16x16x32_bf16 v[108:111], v[188:191], v[220:223], 0
	s_waitcnt lgkmcnt(3)
	v_mfma_f32_16x16x32_bf16 v[96:99], v[164:167], v[228:231], 0
	v_mfma_f32_16x16x32_bf16 v[92:95], v[188:191], v[228:231], 0
	s_waitcnt lgkmcnt(1)
	v_mfma_f32_16x16x32_bf16 v[80:83], v[164:167], v[236:239], 0
	v_mfma_f32_16x16x32_bf16 v[76:79], v[188:191], v[236:239], 0
	v_mfma_f32_16x16x32_bf16 v[128:131], v[168:171], v[216:219], v[128:131]
	v_mfma_f32_16x16x32_bf16 v[124:127], v[192:195], v[216:219], v[124:127]
	v_mfma_f32_16x16x32_bf16 v[112:115], v[168:171], v[224:227], v[112:115]
	v_mfma_f32_16x16x32_bf16 v[108:111], v[192:195], v[224:227], v[108:111]
	v_mfma_f32_16x16x32_bf16 v[96:99], v[168:171], v[232:235], v[96:99]
	v_mfma_f32_16x16x32_bf16 v[92:95], v[192:195], v[232:235], v[92:95]
	s_waitcnt lgkmcnt(0)
	v_mfma_f32_16x16x32_bf16 v[80:83], v[168:171], v[240:243], v[80:83]
	v_mfma_f32_16x16x32_bf16 v[76:79], v[192:195], v[240:243], v[76:79]
	s_setprio 0
	s_setprio 1
	v_mfma_f32_16x16x32_bf16 v[120:123], v[196:199], v[212:215], 0
	v_mfma_f32_16x16x32_bf16 v[116:119], v[204:207], v[212:215], 0
	v_mfma_f32_16x16x32_bf16 v[104:107], v[196:199], v[220:223], 0
	v_mfma_f32_16x16x32_bf16 v[100:103], v[204:207], v[220:223], 0
	v_mfma_f32_16x16x32_bf16 v[88:91], v[196:199], v[228:231], 0
	v_mfma_f32_16x16x32_bf16 v[84:87], v[204:207], v[228:231], 0
	v_mfma_f32_16x16x32_bf16 v[72:75], v[196:199], v[236:239], 0
	v_mfma_f32_16x16x32_bf16 v[68:71], v[204:207], v[236:239], 0
	v_mfma_f32_16x16x32_bf16 v[120:123], v[200:203], v[216:219], v[120:123]
	v_mfma_f32_16x16x32_bf16 v[116:119], v[208:211], v[216:219], v[116:119]
	v_mfma_f32_16x16x32_bf16 v[104:107], v[200:203], v[224:227], v[104:107]
	v_mfma_f32_16x16x32_bf16 v[100:103], v[208:211], v[224:227], v[100:103]
	v_mfma_f32_16x16x32_bf16 v[88:91], v[200:203], v[232:235], v[88:91]
	v_mfma_f32_16x16x32_bf16 v[84:87], v[208:211], v[232:235], v[84:87]
	v_mfma_f32_16x16x32_bf16 v[72:75], v[200:203], v[240:243], v[72:75]
	v_mfma_f32_16x16x32_bf16 v[68:71], v[208:211], v[240:243], v[68:71]
	s_setprio 0
	s_barrier
	s_add_i32 s42, s64, s69
	s_mov_b32 m0, s42
	s_nop 0
	global_load_lds_dwordx4 v140, s[48:49]
	s_add_i32 m0, s42, 0x2000
	s_add_u32 s42, s48, s90
	s_addc_u32 s43, s49, 0
	s_add_i32 s64, s65, s69
	global_load_lds_dwordx4 v144, s[48:49]
	s_mov_b32 m0, s64
	s_nop 0
	global_load_lds_dwordx4 v140, s[42:43]
	s_add_i32 m0, s64, 0x2000
	s_nop 0
	global_load_lds_dwordx4 v144, s[42:43]
	ds_read_b128 v[212:215], v160 offset:16384
	ds_read_b128 v[216:219], v160 offset:17408
	ds_read_b128 v[220:223], v160 offset:18432
	ds_read_b128 v[224:227], v160 offset:19456
	ds_read_b128 v[228:231], v160 offset:20480
	ds_read_b128 v[232:235], v160 offset:21504
	ds_read_b128 v[236:239], v160 offset:22528
	ds_read_b128 v[240:243], v160 offset:23552
	s_waitcnt vmcnt(6)
	s_waitcnt lgkmcnt(0)
	s_barrier
	s_setprio 1
	s_waitcnt lgkmcnt(0)
	v_mfma_f32_16x16x32_bf16 v[64:67], v[164:167], v[212:215], 0
	v_mfma_f32_16x16x32_bf16 v[60:63], v[188:191], v[212:215], 0
	v_mfma_f32_16x16x32_bf16 v[48:51], v[164:167], v[220:223], 0
	v_mfma_f32_16x16x32_bf16 v[44:47], v[188:191], v[220:223], 0
	v_mfma_f32_16x16x32_bf16 v[32:35], v[164:167], v[228:231], 0
	v_mfma_f32_16x16x32_bf16 v[28:31], v[188:191], v[228:231], 0
	v_mfma_f32_16x16x32_bf16 v[16:19], v[164:167], v[236:239], 0
	v_mfma_f32_16x16x32_bf16 v[12:15], v[188:191], v[236:239], 0
	v_mfma_f32_16x16x32_bf16 v[64:67], v[168:171], v[216:219], v[64:67]
	v_mfma_f32_16x16x32_bf16 v[60:63], v[192:195], v[216:219], v[60:63]
	v_mfma_f32_16x16x32_bf16 v[48:51], v[168:171], v[224:227], v[48:51]
	v_mfma_f32_16x16x32_bf16 v[44:47], v[192:195], v[224:227], v[44:47]
	v_mfma_f32_16x16x32_bf16 v[32:35], v[168:171], v[232:235], v[32:35]
	v_mfma_f32_16x16x32_bf16 v[28:31], v[192:195], v[232:235], v[28:31]
	v_mfma_f32_16x16x32_bf16 v[16:19], v[168:171], v[240:243], v[16:19]
	v_mfma_f32_16x16x32_bf16 v[12:15], v[192:195], v[240:243], v[12:15]
	s_setprio 0
	s_setprio 1
	v_mfma_f32_16x16x32_bf16 v[56:59], v[196:199], v[212:215], 0
	v_mfma_f32_16x16x32_bf16 v[52:55], v[204:207], v[212:215], 0
	v_mfma_f32_16x16x32_bf16 v[40:43], v[196:199], v[220:223], 0
	v_mfma_f32_16x16x32_bf16 v[36:39], v[204:207], v[220:223], 0
	v_mfma_f32_16x16x32_bf16 v[24:27], v[196:199], v[228:231], 0
	v_mfma_f32_16x16x32_bf16 v[20:23], v[204:207], v[228:231], 0
	v_mfma_f32_16x16x32_bf16 v[8:11], v[196:199], v[236:239], 0
	v_mfma_f32_16x16x32_bf16 v[4:7], v[204:207], v[236:239], 0
	v_mfma_f32_16x16x32_bf16 v[56:59], v[200:203], v[216:219], v[56:59]
	v_mfma_f32_16x16x32_bf16 v[52:55], v[208:211], v[216:219], v[52:55]
	v_mfma_f32_16x16x32_bf16 v[40:43], v[200:203], v[224:227], v[40:43]
	v_mfma_f32_16x16x32_bf16 v[36:39], v[208:211], v[224:227], v[36:39]
	v_mfma_f32_16x16x32_bf16 v[24:27], v[200:203], v[232:235], v[24:27]
	v_mfma_f32_16x16x32_bf16 v[20:23], v[208:211], v[232:235], v[20:23]
	v_mfma_f32_16x16x32_bf16 v[8:11], v[200:203], v[240:243], v[8:11]
	v_mfma_f32_16x16x32_bf16 v[4:7], v[208:211], v[240:243], v[4:7]
	s_setprio 0
	s_barrier
	s_add_i32 s64, 0, 0x18000
	s_add_u32 s42, s50, s90
	s_addc_u32 s43, s51, 0
	s_mov_b32 m0, s56
	s_nop 0
	global_load_lds_dwordx4 v0, s[50:51]
	s_mov_b32 m0, s57
	s_nop 0
	global_load_lds_dwordx4 v142, s[50:51]
	v_add_u32_e32 v187, s64, v3
	s_add_i32 s65, 0, 0x1c000
	ds_read_b128 v[164:167], v187
	ds_read_b128 v[168:171], v187 offset:1024
	ds_read_b128 v[188:191], v187 offset:2048
	ds_read_b128 v[192:195], v187 offset:3072
	v_add_u32_e32 v187, s65, v3
	ds_read_b128 v[196:199], v187
	ds_read_b128 v[200:203], v187 offset:1024
	ds_read_b128 v[204:207], v187 offset:2048
	ds_read_b128 v[208:211], v187 offset:3072
	s_mov_b32 m0, s58
	s_nop 0
	global_load_lds_dwordx4 v0, s[42:43]
	s_mov_b32 m0, s59
	s_nop 0
	global_load_lds_dwordx4 v142, s[42:43]
	ds_read_b128 v[212:215], v160 offset:32768
	ds_read_b128 v[216:219], v160 offset:33792
	ds_read_b128 v[220:223], v160 offset:34816
	ds_read_b128 v[224:227], v160 offset:35840
	ds_read_b128 v[228:231], v160 offset:36864
	ds_read_b128 v[232:235], v160 offset:37888
	ds_read_b128 v[236:239], v160 offset:38912
	ds_read_b128 v[240:243], v160 offset:39936
	s_waitcnt vmcnt(8)
	s_waitcnt lgkmcnt(8)
	s_barrier
	s_setprio 1
	s_waitcnt lgkmcnt(7)
	v_mfma_f32_16x16x32_bf16 v[128:131], v[164:167], v[212:215], v[128:131]
	v_mfma_f32_16x16x32_bf16 v[124:127], v[188:191], v[212:215], v[124:127]
	s_waitcnt lgkmcnt(5)
	v_mfma_f32_16x16x32_bf16 v[112:115], v[164:167], v[220:223], v[112:115]
	v_mfma_f32_16x16x32_bf16 v[108:111], v[188:191], v[220:223], v[108:111]
	s_waitcnt lgkmcnt(3)
	v_mfma_f32_16x16x32_bf16 v[96:99], v[164:167], v[228:231], v[96:99]
	v_mfma_f32_16x16x32_bf16 v[92:95], v[188:191], v[228:231], v[92:95]
	s_waitcnt lgkmcnt(1)
	v_mfma_f32_16x16x32_bf16 v[80:83], v[164:167], v[236:239], v[80:83]
	v_mfma_f32_16x16x32_bf16 v[76:79], v[188:191], v[236:239], v[76:79]
	v_mfma_f32_16x16x32_bf16 v[128:131], v[168:171], v[216:219], v[128:131]
	v_mfma_f32_16x16x32_bf16 v[124:127], v[192:195], v[216:219], v[124:127]
	v_mfma_f32_16x16x32_bf16 v[112:115], v[168:171], v[224:227], v[112:115]
	v_mfma_f32_16x16x32_bf16 v[108:111], v[192:195], v[224:227], v[108:111]
	v_mfma_f32_16x16x32_bf16 v[96:99], v[168:171], v[232:235], v[96:99]
	v_mfma_f32_16x16x32_bf16 v[92:95], v[192:195], v[232:235], v[92:95]
	s_waitcnt lgkmcnt(0)
	v_mfma_f32_16x16x32_bf16 v[80:83], v[168:171], v[240:243], v[80:83]
	v_mfma_f32_16x16x32_bf16 v[76:79], v[192:195], v[240:243], v[76:79]
	s_setprio 0
	s_setprio 1
	v_mfma_f32_16x16x32_bf16 v[120:123], v[196:199], v[212:215], v[120:123]
	v_mfma_f32_16x16x32_bf16 v[116:119], v[204:207], v[212:215], v[116:119]
	v_mfma_f32_16x16x32_bf16 v[104:107], v[196:199], v[220:223], v[104:107]
	v_mfma_f32_16x16x32_bf16 v[100:103], v[204:207], v[220:223], v[100:103]
	v_mfma_f32_16x16x32_bf16 v[88:91], v[196:199], v[228:231], v[88:91]
	v_mfma_f32_16x16x32_bf16 v[84:87], v[204:207], v[228:231], v[84:87]
	v_mfma_f32_16x16x32_bf16 v[72:75], v[196:199], v[236:239], v[72:75]
	v_mfma_f32_16x16x32_bf16 v[68:71], v[204:207], v[236:239], v[68:71]
	v_mfma_f32_16x16x32_bf16 v[120:123], v[200:203], v[216:219], v[120:123]
	v_mfma_f32_16x16x32_bf16 v[116:119], v[208:211], v[216:219], v[116:119]
	v_mfma_f32_16x16x32_bf16 v[104:107], v[200:203], v[224:227], v[104:107]
	v_mfma_f32_16x16x32_bf16 v[100:103], v[208:211], v[224:227], v[100:103]
	v_mfma_f32_16x16x32_bf16 v[88:91], v[200:203], v[232:235], v[88:91]
	v_mfma_f32_16x16x32_bf16 v[84:87], v[208:211], v[232:235], v[84:87]
	v_mfma_f32_16x16x32_bf16 v[72:75], v[200:203], v[240:243], v[72:75]
	v_mfma_f32_16x16x32_bf16 v[68:71], v[208:211], v[240:243], v[68:71]
	s_setprio 0
	s_barrier
	s_add_u32 s42, s48, 0x80
	s_addc_u32 s43, s49, 0
	s_add_i32 s50, s64, s69
	s_mov_b32 m0, s50
	s_nop 0
	global_load_lds_dwordx4 v140, s[42:43]
	s_add_i32 m0, s50, 0x2000
	s_nop 0
	global_load_lds_dwordx4 v144, s[42:43]
	s_add_u32 s42, s48, s53
	s_addc_u32 s43, s49, 0
	s_add_i32 s48, s65, s69
	s_mov_b32 m0, s48
	s_nop 0
	global_load_lds_dwordx4 v140, s[42:43]
	s_add_i32 m0, s48, 0x2000
	s_nop 0
	global_load_lds_dwordx4 v144, s[42:43]
	ds_read_b128 v[212:215], v160 offset:49152
	ds_read_b128 v[216:219], v160 offset:50176
	ds_read_b128 v[220:223], v160 offset:51200
	ds_read_b128 v[224:227], v160 offset:52224
	ds_read_b128 v[228:231], v160 offset:53248
	ds_read_b128 v[232:235], v160 offset:54272
	ds_read_b128 v[236:239], v160 offset:55296
	ds_read_b128 v[240:243], v160 offset:56320
	s_waitcnt vmcnt(6)
	s_waitcnt lgkmcnt(0)
	s_barrier
	s_setprio 1
	s_waitcnt lgkmcnt(0)
	v_mfma_f32_16x16x32_bf16 v[64:67], v[164:167], v[212:215], v[64:67]
	v_mfma_f32_16x16x32_bf16 v[60:63], v[188:191], v[212:215], v[60:63]
	v_mfma_f32_16x16x32_bf16 v[48:51], v[164:167], v[220:223], v[48:51]
	v_mfma_f32_16x16x32_bf16 v[44:47], v[188:191], v[220:223], v[44:47]
	v_mfma_f32_16x16x32_bf16 v[32:35], v[164:167], v[228:231], v[32:35]
	v_mfma_f32_16x16x32_bf16 v[28:31], v[188:191], v[228:231], v[28:31]
	v_mfma_f32_16x16x32_bf16 v[16:19], v[164:167], v[236:239], v[16:19]
	v_mfma_f32_16x16x32_bf16 v[12:15], v[188:191], v[236:239], v[12:15]
	v_mfma_f32_16x16x32_bf16 v[64:67], v[168:171], v[216:219], v[64:67]
	v_mfma_f32_16x16x32_bf16 v[60:63], v[192:195], v[216:219], v[60:63]
	v_mfma_f32_16x16x32_bf16 v[48:51], v[168:171], v[224:227], v[48:51]
	v_mfma_f32_16x16x32_bf16 v[44:47], v[192:195], v[224:227], v[44:47]
	v_mfma_f32_16x16x32_bf16 v[32:35], v[168:171], v[232:235], v[32:35]
	v_mfma_f32_16x16x32_bf16 v[28:31], v[192:195], v[232:235], v[28:31]
	v_mfma_f32_16x16x32_bf16 v[16:19], v[168:171], v[240:243], v[16:19]
	v_mfma_f32_16x16x32_bf16 v[12:15], v[192:195], v[240:243], v[12:15]
	s_setprio 0
	s_setprio 1
	v_mfma_f32_16x16x32_bf16 v[56:59], v[196:199], v[212:215], v[56:59]
	v_mfma_f32_16x16x32_bf16 v[52:55], v[204:207], v[212:215], v[52:55]
	v_mfma_f32_16x16x32_bf16 v[40:43], v[196:199], v[220:223], v[40:43]
	v_mfma_f32_16x16x32_bf16 v[36:39], v[204:207], v[220:223], v[36:39]
	v_mfma_f32_16x16x32_bf16 v[24:27], v[196:199], v[228:231], v[24:27]
	v_mfma_f32_16x16x32_bf16 v[20:23], v[204:207], v[228:231], v[20:23]
	v_mfma_f32_16x16x32_bf16 v[8:11], v[196:199], v[236:239], v[8:11]
	v_mfma_f32_16x16x32_bf16 v[4:7], v[204:207], v[236:239], v[4:7]
	v_mfma_f32_16x16x32_bf16 v[56:59], v[200:203], v[216:219], v[56:59]
	v_mfma_f32_16x16x32_bf16 v[52:55], v[208:211], v[216:219], v[52:55]
	v_mfma_f32_16x16x32_bf16 v[40:43], v[200:203], v[224:227], v[40:43]
	v_mfma_f32_16x16x32_bf16 v[36:39], v[208:211], v[224:227], v[36:39]
	v_mfma_f32_16x16x32_bf16 v[24:27], v[200:203], v[232:235], v[24:27]
	v_mfma_f32_16x16x32_bf16 v[20:23], v[208:211], v[232:235], v[20:23]
	v_mfma_f32_16x16x32_bf16 v[8:11], v[200:203], v[240:243], v[8:11]
	v_mfma_f32_16x16x32_bf16 v[4:7], v[208:211], v[240:243], v[4:7]
	s_setprio 0
	s_barrier
	s_add_i32 s63, s63, 2
	s_add_u32 s28, s28, 0x100
	s_addc_u32 s29, s29, 0
	s_cmp_gt_u32 s63, s55
	s_mov_b64 s[42:43], s[44:45]

.Lg1_loop:
	s_add_u32 s44, s42, 0x100
	s_addc_u32 s45, s43, 0
	s_cmp_eq_u32 s63, s54
	s_cselect_b32 s50, s26, s44
	s_cselect_b32 s51, s5, s45
	s_cselect_b32 s48, s27, s28
	s_cselect_b32 s49, s23, s29
	s_add_i32 s64, 0, 0x10000
	s_add_u32 s46, s42, 0x80
	s_addc_u32 s47, s43, 0
	s_add_u32 s42, s42, s53
	s_addc_u32 s43, s43, 0
	s_mov_b32 m0, s60
	s_nop 0
	global_load_lds_dwordx4 v0, s[46:47]
	s_mov_b32 m0, s61
	s_nop 0
	global_load_lds_dwordx4 v142, s[46:47]
	v_add_u32_e32 v187, s64, v3
	s_add_i32 s65, 0, 0x14000
	ds_read_b128 v[164:167], v187
	ds_read_b128 v[168:171], v187 offset:1024
	ds_read_b128 v[188:191], v187 offset:2048
	ds_read_b128 v[192:195], v187 offset:3072
	v_add_u32_e32 v187, s65, v3
	ds_read_b128 v[196:199], v187
	ds_read_b128 v[200:203], v187 offset:1024
	ds_read_b128 v[204:207], v187 offset:2048
	ds_read_b128 v[208:211], v187 offset:3072
	s_add_i32 m0, s56, 0xc000
	s_nop 0
	global_load_lds_dwordx4 v0, s[42:43]
	s_add_i32 m0, s56, 0xe000
	s_nop 0
	global_load_lds_dwordx4 v142, s[42:43]
	ds_read_b128 v[212:215], v160
	ds_read_b128 v[216:219], v160 offset:1024
	ds_read_b128 v[220:223], v160 offset:2048
	ds_read_b128 v[224:227], v160 offset:3072
	ds_read_b128 v[228:231], v160 offset:4096
	ds_read_b128 v[232:235], v160 offset:5120
	ds_read_b128 v[236:239], v160 offset:6144
	ds_read_b128 v[240:243], v160 offset:7168
	s_waitcnt vmcnt(8)
	s_waitcnt lgkmcnt(8)
	s_barrier
	s_setprio 1
	s_waitcnt lgkmcnt(7)
	v_mfma_f32_16x16x32_bf16 v[128:131], v[164:167], v[212:215], v[128:131]
	v_mfma_f32_16x16x32_bf16 v[124:127], v[188:191], v[212:215], v[124:127]
	s_waitcnt lgkmcnt(5)
	v_mfma_f32_16x16x32_bf16 v[112:115], v[164:167], v[220:223], v[112:115]
	v_mfma_f32_16x16x32_bf16 v[108:111], v[188:191], v[220:223], v[108:111]
	s_waitcnt lgkmcnt(3)
	v_mfma_f32_16x16x32_bf16 v[96:99], v[164:167], v[228:231], v[96:99]
	v_mfma_f32_16x16x32_bf16 v[92:95], v[188:191], v[228:231], v[92:95]
	s_waitcnt lgkmcnt(1)
	v_mfma_f32_16x16x32_bf16 v[80:83], v[164:167], v[236:239], v[80:83]
	v_mfma_f32_16x16x32_bf16 v[76:79], v[188:191], v[236:239], v[76:79]
	v_mfma_f32_16x16x32_bf16 v[128:131], v[168:171], v[216:219], v[128:131]
	v_mfma_f32_16x16x32_bf16 v[124:127], v[192:195], v[216:219], v[124:127]
	v_mfma_f32_16x16x32_bf16 v[112:115], v[168:171], v[224:227], v[112:115]
	v_mfma_f32_16x16x32_bf16 v[108:111], v[192:195], v[224:227], v[108:111]
	v_mfma_f32_16x16x32_bf16 v[96:99], v[168:171], v[232:235], v[96:99]
	v_mfma_f32_16x16x32_bf16 v[92:95], v[192:195], v[232:235], v[92:95]
	s_waitcnt lgkmcnt(0)
	v_mfma_f32_16x16x32_bf16 v[80:83], v[168:171], v[240:243], v[80:83]
	v_mfma_f32_16x16x32_bf16 v[76:79], v[192:195], v[240:243], v[76:79]
	s_setprio 0
	s_setprio 1
	v_mfma_f32_16x16x32_bf16 v[120:123], v[196:199], v[212:215], v[120:123]
	v_mfma_f32_16x16x32_bf16 v[116:119], v[204:207], v[212:215], v[116:119]
	v_mfma_f32_16x16x32_bf16 v[104:107], v[196:199], v[220:223], v[104:107]
	v_mfma_f32_16x16x32_bf16 v[100:103], v[204:207], v[220:223], v[100:103]
	v_mfma_f32_16x16x32_bf16 v[88:91], v[196:199], v[228:231], v[88:91]
	v_mfma_f32_16x16x32_bf16 v[84:87], v[204:207], v[228:231], v[84:87]
	v_mfma_f32_16x16x32_bf16 v[72:75], v[196:199], v[236:239], v[72:75]
	v_mfma_f32_16x16x32_bf16 v[68:71], v[204:207], v[236:239], v[68:71]
	v_mfma_f32_16x16x32_bf16 v[120:123], v[200:203], v[216:219], v[120:123]
	v_mfma_f32_16x16x32_bf16 v[116:119], v[208:211], v[216:219], v[116:119]
	v_mfma_f32_16x16x32_bf16 v[104:107], v[200:203], v[224:227], v[104:107]
	v_mfma_f32_16x16x32_bf16 v[100:103], v[208:211], v[224:227], v[100:103]
	v_mfma_f32_16x16x32_bf16 v[88:91], v[200:203], v[232:235], v[88:91]
	v_mfma_f32_16x16x32_bf16 v[84:87], v[208:211], v[232:235], v[84:87]
	v_mfma_f32_16x16x32_bf16 v[72:75], v[200:203], v[240:243], v[72:75]
	v_mfma_f32_16x16x32_bf16 v[68:71], v[208:211], v[240:243], v[68:71]
	s_setprio 0
	s_barrier
	s_add_i32 s42, s64, s69
	s_mov_b32 m0, s42
	s_nop 0
	global_load_lds_dwordx4 v140, s[48:49]
	s_add_i32 m0, s42, 0x2000
	s_add_u32 s42, s48, s90
	s_addc_u32 s43, s49, 0
	s_add_i32 s64, s65, s69
	global_load_lds_dwordx4 v144, s[48:49]
	s_mov_b32 m0, s64
	s_nop 0
	global_load_lds_dwordx4 v140, s[42:43]
	s_add_i32 m0, s64, 0x2000
	s_nop 0
	global_load_lds_dwordx4 v144, s[42:43]
	ds_read_b128 v[212:215], v160 offset:16384
	ds_read_b128 v[216:219], v160 offset:17408
	ds_read_b128 v[220:223], v160 offset:18432
	ds_read_b128 v[224:227], v160 offset:19456
	ds_read_b128 v[228:231], v160 offset:20480
	ds_read_b128 v[232:235], v160 offset:21504
	ds_read_b128 v[236:239], v160 offset:22528
	ds_read_b128 v[240:243], v160 offset:23552
	s_waitcnt vmcnt(6)
	s_waitcnt lgkmcnt(0)
	s_barrier
	s_setprio 1
	s_waitcnt lgkmcnt(0)
	v_mfma_f32_16x16x32_bf16 v[64:67], v[164:167], v[212:215], v[64:67]
	v_mfma_f32_16x16x32_bf16 v[60:63], v[188:191], v[212:215], v[60:63]
	v_mfma_f32_16x16x32_bf16 v[48:51], v[164:167], v[220:223], v[48:51]
	v_mfma_f32_16x16x32_bf16 v[44:47], v[188:191], v[220:223], v[44:47]
	v_mfma_f32_16x16x32_bf16 v[32:35], v[164:167], v[228:231], v[32:35]
	v_mfma_f32_16x16x32_bf16 v[28:31], v[188:191], v[228:231], v[28:31]
	v_mfma_f32_16x16x32_bf16 v[16:19], v[164:167], v[236:239], v[16:19]
	v_mfma_f32_16x16x32_bf16 v[12:15], v[188:191], v[236:239], v[12:15]
	v_mfma_f32_16x16x32_bf16 v[64:67], v[168:171], v[216:219], v[64:67]
	v_mfma_f32_16x16x32_bf16 v[60:63], v[192:195], v[216:219], v[60:63]
	v_mfma_f32_16x16x32_bf16 v[48:51], v[168:171], v[224:227], v[48:51]
	v_mfma_f32_16x16x32_bf16 v[44:47], v[192:195], v[224:227], v[44:47]
	v_mfma_f32_16x16x32_bf16 v[32:35], v[168:171], v[232:235], v[32:35]
	v_mfma_f32_16x16x32_bf16 v[28:31], v[192:195], v[232:235], v[28:31]
	v_mfma_f32_16x16x32_bf16 v[16:19], v[168:171], v[240:243], v[16:19]
	v_mfma_f32_16x16x32_bf16 v[12:15], v[192:195], v[240:243], v[12:15]
	s_setprio 0
	s_setprio 1
	v_mfma_f32_16x16x32_bf16 v[56:59], v[196:199], v[212:215], v[56:59]
	v_mfma_f32_16x16x32_bf16 v[52:55], v[204:207], v[212:215], v[52:55]
	v_mfma_f32_16x16x32_bf16 v[40:43], v[196:199], v[220:223], v[40:43]
	v_mfma_f32_16x16x32_bf16 v[36:39], v[204:207], v[220:223], v[36:39]
	v_mfma_f32_16x16x32_bf16 v[24:27], v[196:199], v[228:231], v[24:27]
	v_mfma_f32_16x16x32_bf16 v[20:23], v[204:207], v[228:231], v[20:23]
	v_mfma_f32_16x16x32_bf16 v[8:11], v[196:199], v[236:239], v[8:11]
	v_mfma_f32_16x16x32_bf16 v[4:7], v[204:207], v[236:239], v[4:7]
	v_mfma_f32_16x16x32_bf16 v[56:59], v[200:203], v[216:219], v[56:59]
	v_mfma_f32_16x16x32_bf16 v[52:55], v[208:211], v[216:219], v[52:55]
	v_mfma_f32_16x16x32_bf16 v[40:43], v[200:203], v[224:227], v[40:43]
	v_mfma_f32_16x16x32_bf16 v[36:39], v[208:211], v[224:227], v[36:39]
	v_mfma_f32_16x16x32_bf16 v[24:27], v[200:203], v[232:235], v[24:27]
	v_mfma_f32_16x16x32_bf16 v[20:23], v[208:211], v[232:235], v[20:23]
	v_mfma_f32_16x16x32_bf16 v[8:11], v[200:203], v[240:243], v[8:11]
	v_mfma_f32_16x16x32_bf16 v[4:7], v[208:211], v[240:243], v[4:7]
	s_setprio 0
	s_barrier
	s_add_i32 s64, 0, 0x18000
	s_add_u32 s42, s50, s90
	s_addc_u32 s43, s51, 0
	s_mov_b32 m0, s56
	s_nop 0
	global_load_lds_dwordx4 v0, s[50:51]
	s_mov_b32 m0, s57
	s_nop 0
	global_load_lds_dwordx4 v142, s[50:51]
	v_add_u32_e32 v187, s64, v3
	s_add_i32 s65, 0, 0x1c000
	ds_read_b128 v[164:167], v187
	ds_read_b128 v[168:171], v187 offset:1024
	ds_read_b128 v[188:191], v187 offset:2048
	ds_read_b128 v[192:195], v187 offset:3072
	v_add_u32_e32 v187, s65, v3
	ds_read_b128 v[196:199], v187
	ds_read_b128 v[200:203], v187 offset:1024
	ds_read_b128 v[204:207], v187 offset:2048
	ds_read_b128 v[208:211], v187 offset:3072
	s_mov_b32 m0, s58
	s_nop 0
	global_load_lds_dwordx4 v0, s[42:43]
	s_mov_b32 m0, s59
	s_nop 0
	global_load_lds_dwordx4 v142, s[42:43]
	ds_read_b128 v[212:215], v160 offset:32768
	ds_read_b128 v[216:219], v160 offset:33792
	ds_read_b128 v[220:223], v160 offset:34816
	ds_read_b128 v[224:227], v160 offset:35840
	ds_read_b128 v[228:231], v160 offset:36864
	ds_read_b128 v[232:235], v160 offset:37888
	ds_read_b128 v[236:239], v160 offset:38912
	ds_read_b128 v[240:243], v160 offset:39936
	s_waitcnt vmcnt(8)
	s_waitcnt lgkmcnt(8)
	s_barrier
	s_setprio 1
	s_waitcnt lgkmcnt(7)
	v_mfma_f32_16x16x32_bf16 v[128:131], v[164:167], v[212:215], v[128:131]
	v_mfma_f32_16x16x32_bf16 v[124:127], v[188:191], v[212:215], v[124:127]
	s_waitcnt lgkmcnt(5)
	v_mfma_f32_16x16x32_bf16 v[112:115], v[164:167], v[220:223], v[112:115]
	v_mfma_f32_16x16x32_bf16 v[108:111], v[188:191], v[220:223], v[108:111]
	s_waitcnt lgkmcnt(3)
	v_mfma_f32_16x16x32_bf16 v[96:99], v[164:167], v[228:231], v[96:99]
	v_mfma_f32_16x16x32_bf16 v[92:95], v[188:191], v[228:231], v[92:95]
	s_waitcnt lgkmcnt(1)
	v_mfma_f32_16x16x32_bf16 v[80:83], v[164:167], v[236:239], v[80:83]
	v_mfma_f32_16x16x32_bf16 v[76:79], v[188:191], v[236:239], v[76:79]
	v_mfma_f32_16x16x32_bf16 v[128:131], v[168:171], v[216:219], v[128:131]
	v_mfma_f32_16x16x32_bf16 v[124:127], v[192:195], v[216:219], v[124:127]
	v_mfma_f32_16x16x32_bf16 v[112:115], v[168:171], v[224:227], v[112:115]
	v_mfma_f32_16x16x32_bf16 v[108:111], v[192:195], v[224:227], v[108:111]
	v_mfma_f32_16x16x32_bf16 v[96:99], v[168:171], v[232:235], v[96:99]
	v_mfma_f32_16x16x32_bf16 v[92:95], v[192:195], v[232:235], v[92:95]
	s_waitcnt lgkmcnt(0)
	v_mfma_f32_16x16x32_bf16 v[80:83], v[168:171], v[240:243], v[80:83]
	v_mfma_f32_16x16x32_bf16 v[76:79], v[192:195], v[240:243], v[76:79]
	s_setprio 0
	s_setprio 1
	v_mfma_f32_16x16x32_bf16 v[120:123], v[196:199], v[212:215], v[120:123]
	v_mfma_f32_16x16x32_bf16 v[116:119], v[204:207], v[212:215], v[116:119]
	v_mfma_f32_16x16x32_bf16 v[104:107], v[196:199], v[220:223], v[104:107]
	v_mfma_f32_16x16x32_bf16 v[100:103], v[204:207], v[220:223], v[100:103]
	v_mfma_f32_16x16x32_bf16 v[88:91], v[196:199], v[228:231], v[88:91]
	v_mfma_f32_16x16x32_bf16 v[84:87], v[204:207], v[228:231], v[84:87]
	v_mfma_f32_16x16x32_bf16 v[72:75], v[196:199], v[236:239], v[72:75]
	v_mfma_f32_16x16x32_bf16 v[68:71], v[204:207], v[236:239], v[68:71]
	v_mfma_f32_16x16x32_bf16 v[120:123], v[200:203], v[216:219], v[120:123]
	v_mfma_f32_16x16x32_bf16 v[116:119], v[208:211], v[216:219], v[116:119]
	v_mfma_f32_16x16x32_bf16 v[104:107], v[200:203], v[224:227], v[104:107]
	v_mfma_f32_16x16x32_bf16 v[100:103], v[208:211], v[224:227], v[100:103]
	v_mfma_f32_16x16x32_bf16 v[88:91], v[200:203], v[232:235], v[88:91]
	v_mfma_f32_16x16x32_bf16 v[84:87], v[208:211], v[232:235], v[84:87]
	v_mfma_f32_16x16x32_bf16 v[72:75], v[200:203], v[240:243], v[72:75]
	v_mfma_f32_16x16x32_bf16 v[68:71], v[208:211], v[240:243], v[68:71]
	s_setprio 0
	s_barrier
	s_add_u32 s42, s48, 0x80
	s_addc_u32 s43, s49, 0
	s_add_i32 s50, s64, s69
	s_mov_b32 m0, s50
	s_nop 0
	global_load_lds_dwordx4 v140, s[42:43]
	s_add_i32 m0, s50, 0x2000
	s_nop 0
	global_load_lds_dwordx4 v144, s[42:43]
	s_add_u32 s42, s48, s53
	s_addc_u32 s43, s49, 0
	s_add_i32 s48, s65, s69
	s_mov_b32 m0, s48
	s_nop 0
	global_load_lds_dwordx4 v140, s[42:43]
	s_add_i32 m0, s48, 0x2000
	s_nop 0
	global_load_lds_dwordx4 v144, s[42:43]
	ds_read_b128 v[212:215], v160 offset:49152
	ds_read_b128 v[216:219], v160 offset:50176
	ds_read_b128 v[220:223], v160 offset:51200
	ds_read_b128 v[224:227], v160 offset:52224
	ds_read_b128 v[228:231], v160 offset:53248
	ds_read_b128 v[232:235], v160 offset:54272
	ds_read_b128 v[236:239], v160 offset:55296
	ds_read_b128 v[240:243], v160 offset:56320
	s_waitcnt vmcnt(6)
	s_waitcnt lgkmcnt(0)
	s_barrier
	s_setprio 1
	s_waitcnt lgkmcnt(0)
	v_mfma_f32_16x16x32_bf16 v[64:67], v[164:167], v[212:215], v[64:67]
	v_mfma_f32_16x16x32_bf16 v[60:63], v[188:191], v[212:215], v[60:63]
	v_mfma_f32_16x16x32_bf16 v[48:51], v[164:167], v[220:223], v[48:51]
	v_mfma_f32_16x16x32_bf16 v[44:47], v[188:191], v[220:223], v[44:47]
	v_mfma_f32_16x16x32_bf16 v[32:35], v[164:167], v[228:231], v[32:35]
	v_mfma_f32_16x16x32_bf16 v[28:31], v[188:191], v[228:231], v[28:31]
	v_mfma_f32_16x16x32_bf16 v[16:19], v[164:167], v[236:239], v[16:19]
	v_mfma_f32_16x16x32_bf16 v[12:15], v[188:191], v[236:239], v[12:15]
	v_mfma_f32_16x16x32_bf16 v[64:67], v[168:171], v[216:219], v[64:67]
	v_mfma_f32_16x16x32_bf16 v[60:63], v[192:195], v[216:219], v[60:63]
	v_mfma_f32_16x16x32_bf16 v[48:51], v[168:171], v[224:227], v[48:51]
	v_mfma_f32_16x16x32_bf16 v[44:47], v[192:195], v[224:227], v[44:47]
	v_mfma_f32_16x16x32_bf16 v[32:35], v[168:171], v[232:235], v[32:35]
	v_mfma_f32_16x16x32_bf16 v[28:31], v[192:195], v[232:235], v[28:31]
	v_mfma_f32_16x16x32_bf16 v[16:19], v[168:171], v[240:243], v[16:19]
	v_mfma_f32_16x16x32_bf16 v[12:15], v[192:195], v[240:243], v[12:15]
	s_setprio 0
	s_setprio 1
	v_mfma_f32_16x16x32_bf16 v[56:59], v[196:199], v[212:215], v[56:59]
	v_mfma_f32_16x16x32_bf16 v[52:55], v[204:207], v[212:215], v[52:55]
	v_mfma_f32_16x16x32_bf16 v[40:43], v[196:199], v[220:223], v[40:43]
	v_mfma_f32_16x16x32_bf16 v[36:39], v[204:207], v[220:223], v[36:39]
	v_mfma_f32_16x16x32_bf16 v[24:27], v[196:199], v[228:231], v[24:27]
	v_mfma_f32_16x16x32_bf16 v[20:23], v[204:207], v[228:231], v[20:23]
	v_mfma_f32_16x16x32_bf16 v[8:11], v[196:199], v[236:239], v[8:11]
	v_mfma_f32_16x16x32_bf16 v[4:7], v[204:207], v[236:239], v[4:7]
	v_mfma_f32_16x16x32_bf16 v[56:59], v[200:203], v[216:219], v[56:59]
	v_mfma_f32_16x16x32_bf16 v[52:55], v[208:211], v[216:219], v[52:55]
	v_mfma_f32_16x16x32_bf16 v[40:43], v[200:203], v[224:227], v[40:43]
	v_mfma_f32_16x16x32_bf16 v[36:39], v[208:211], v[224:227], v[36:39]
	v_mfma_f32_16x16x32_bf16 v[24:27], v[200:203], v[232:235], v[24:27]
	v_mfma_f32_16x16x32_bf16 v[20:23], v[208:211], v[232:235], v[20:23]
	v_mfma_f32_16x16x32_bf16 v[8:11], v[200:203], v[240:243], v[8:11]
	v_mfma_f32_16x16x32_bf16 v[4:7], v[208:211], v[240:243], v[4:7]
	s_setprio 0
	s_barrier
	s_add_i32 s63, s63, 2
	s_add_u32 s28, s28, 0x100
	s_addc_u32 s29, s29, 0
	s_cmp_gt_u32 s63, s55
	s_mov_b64 s[42:43], s[44:45]
	s_cbranch_scc0 .Lg1_loop
	v_readlane_b32 s5, v250, 0
	v_readlane_b32 s23, v250, 1
	v_readlane_b32 s26, v250, 2
	v_readlane_b32 s27, v250, 3
	v_readlane_b32 s28, v250, 4
	v_readlane_b32 s29, v250, 5
	v_readlane_b32 s42, v250, 6
	v_readlane_b32 s43, v250, 7
	v_readlane_b32 s44, v250, 8
	v_readlane_b32 s45, v250, 9
	v_readlane_b32 s46, v250, 10
	v_readlane_b32 s47, v250, 11
	v_readlane_b32 s48, v250, 12
	v_readlane_b32 s49, v250, 13
	v_readlane_b32 s50, v250, 14
	v_readlane_b32 s51, v250, 15
	v_readlane_b32 s53, v250, 16
	v_readlane_b32 s54, v250, 17
	v_readlane_b32 s55, v250, 18
	v_readlane_b32 s56, v250, 19
	v_readlane_b32 s57, v250, 20
	v_readlane_b32 s58, v250, 21
	v_readlane_b32 s59, v250, 22
	v_readlane_b32 s60, v250, 23
	v_readlane_b32 s61, v250, 24
	v_readlane_b32 s63, v250, 25
	v_readlane_b32 s64, v250, 26
	v_readlane_b32 s65, v250, 27
	s_and_b64 vcc, exec, s[14:15]
	s_cbranch_vccz .LBB0_419
	s_barrier

.LBB0_499:
	s_ashr_i32 s5, s4, 31
	s_lshl_b64 s[24:25], s[4:5], 19
	s_add_u32 s24, s52, s24
	s_addc_u32 s25, s53, s25
	s_and_b64 s[26:27], s[40:41], exec
	s_cselect_b32 s5, s25, s43
	s_cselect_b32 s26, s24, s42
	s_ashr_i32 s23, s22, 31
	s_lshl_b64 s[28:29], s[22:23], 19
	s_add_u32 s36, s54, s28
	s_addc_u32 s37, s55, s29
	s_and_b64 s[28:29], s[40:41], exec
	s_cselect_b32 s23, s37, s45
	s_cselect_b32 s27, s36, s44
	s_add_u32 s28, s44, 0x100
	v_mov_b32_e32 v4, 0
	s_addc_u32 s29, s45, 0
	s_mov_b32 s63, -2
	s_add_u32 s44, s42, 0x100
	s_addc_u32 s45, s43, 0
	s_cmp_eq_u32 s63, 12
	s_cselect_b32 s50, s26, s44
	s_cselect_b32 s51, s5, s45
	s_cselect_b32 s48, s27, s28
	s_cselect_b32 s49, s23, s29
	s_add_i32 s64, 0, 0x10000
	s_add_u32 s46, s42, 0x80
	s_addc_u32 s47, s43, 0
	s_add_u32 s42, s42, 0x40080
	s_addc_u32 s43, s43, 0
	s_mov_b32 m0, s60
	s_nop 0
	global_load_lds_dwordx4 v144, s[46:47]
	s_mov_b32 m0, s61
	s_nop 0
	global_load_lds_dwordx4 v140, s[46:47]
	v_add_u32_e32 v138, s64, v3
	s_add_i32 s65, 0, 0x14000
	ds_read_b128 v[146:149], v138
	ds_read_b128 v[150:153], v138 offset:1024
	ds_read_b128 v[154:157], v138 offset:2048
	ds_read_b128 v[158:161], v138 offset:3072
	v_add_u32_e32 v138, s65, v3
	ds_read_b128 v[162:165], v138
	ds_read_b128 v[166:169], v138 offset:1024
	ds_read_b128 v[170:173], v138 offset:2048
	ds_read_b128 v[186:189], v138 offset:3072
	s_add_i32 m0, s56, 0xc000
	s_nop 0
	global_load_lds_dwordx4 v144, s[42:43]
	s_add_i32 m0, s56, 0xe000
	s_nop 0
	global_load_lds_dwordx4 v140, s[42:43]
	ds_read_b128 v[190:193], v132
	ds_read_b128 v[194:197], v132 offset:1024
	ds_read_b128 v[198:201], v132 offset:2048
	ds_read_b128 v[202:205], v132 offset:3072
	ds_read_b128 v[206:209], v132 offset:4096
	ds_read_b128 v[210:213], v132 offset:5120
	ds_read_b128 v[214:217], v132 offset:6144
	ds_read_b128 v[218:221], v132 offset:7168
	s_waitcnt vmcnt(8)
	s_waitcnt lgkmcnt(8)
	s_barrier
	s_setprio 1
	s_waitcnt lgkmcnt(7)
	v_mfma_f32_16x16x32_bf16 v[128:131], v[146:149], v[190:193], 0
	v_mfma_f32_16x16x32_bf16 v[124:127], v[154:157], v[190:193], 0
	s_waitcnt lgkmcnt(5)
	v_mfma_f32_16x16x32_bf16 v[112:115], v[146:149], v[198:201], 0
	v_mfma_f32_16x16x32_bf16 v[108:111], v[154:157], v[198:201], 0
	s_waitcnt lgkmcnt(3)
	v_mfma_f32_16x16x32_bf16 v[96:99], v[146:149], v[206:209], 0
	v_mfma_f32_16x16x32_bf16 v[92:95], v[154:157], v[206:209], 0
	s_waitcnt lgkmcnt(1)
	v_mfma_f32_16x16x32_bf16 v[80:83], v[146:149], v[214:217], 0
	v_mfma_f32_16x16x32_bf16 v[76:79], v[154:157], v[214:217], 0
	v_mfma_f32_16x16x32_bf16 v[128:131], v[150:153], v[194:197], v[128:131]
	v_mfma_f32_16x16x32_bf16 v[124:127], v[158:161], v[194:197], v[124:127]
	v_mfma_f32_16x16x32_bf16 v[112:115], v[150:153], v[202:205], v[112:115]
	v_mfma_f32_16x16x32_bf16 v[108:111], v[158:161], v[202:205], v[108:111]
	v_mfma_f32_16x16x32_bf16 v[96:99], v[150:153], v[210:213], v[96:99]
	v_mfma_f32_16x16x32_bf16 v[92:95], v[158:161], v[210:213], v[92:95]
	s_waitcnt lgkmcnt(0)
	v_mfma_f32_16x16x32_bf16 v[80:83], v[150:153], v[218:221], v[80:83]
	v_mfma_f32_16x16x32_bf16 v[76:79], v[158:161], v[218:221], v[76:79]
	s_setprio 0
	s_setprio 1
	v_mfma_f32_16x16x32_bf16 v[120:123], v[162:165], v[190:193], 0
	v_mfma_f32_16x16x32_bf16 v[116:119], v[170:173], v[190:193], 0
	v_mfma_f32_16x16x32_bf16 v[104:107], v[162:165], v[198:201], 0
	v_mfma_f32_16x16x32_bf16 v[100:103], v[170:173], v[198:201], 0
	v_mfma_f32_16x16x32_bf16 v[88:91], v[162:165], v[206:209], 0
	v_mfma_f32_16x16x32_bf16 v[84:87], v[170:173], v[206:209], 0
	v_mfma_f32_16x16x32_bf16 v[72:75], v[162:165], v[214:217], 0
	v_mfma_f32_16x16x32_bf16 v[68:71], v[170:173], v[214:217], 0
	v_mfma_f32_16x16x32_bf16 v[120:123], v[166:169], v[194:197], v[120:123]
	v_mfma_f32_16x16x32_bf16 v[116:119], v[186:189], v[194:197], v[116:119]
	v_mfma_f32_16x16x32_bf16 v[104:107], v[166:169], v[202:205], v[104:107]
	v_mfma_f32_16x16x32_bf16 v[100:103], v[186:189], v[202:205], v[100:103]
	v_mfma_f32_16x16x32_bf16 v[88:91], v[166:169], v[210:213], v[88:91]
	v_mfma_f32_16x16x32_bf16 v[84:87], v[186:189], v[210:213], v[84:87]
	v_mfma_f32_16x16x32_bf16 v[72:75], v[166:169], v[218:221], v[72:75]
	v_mfma_f32_16x16x32_bf16 v[68:71], v[186:189], v[218:221], v[68:71]
	s_setprio 0
	s_barrier
	s_add_i32 s42, s64, s69
	s_mov_b32 m0, s42
	s_nop 0
	global_load_lds_dwordx4 v142, s[48:49]
	s_add_i32 m0, s42, 0x2000
	s_add_u32 s42, s48, 0x40000
	s_addc_u32 s43, s49, 0
	s_add_i32 s64, s65, s69
	global_load_lds_dwordx4 v0, s[48:49]
	s_mov_b32 m0, s64
	s_nop 0
	global_load_lds_dwordx4 v142, s[42:43]
	s_add_i32 m0, s64, 0x2000
	s_nop 0
	global_load_lds_dwordx4 v0, s[42:43]
	ds_read_b128 v[190:193], v132 offset:16384
	ds_read_b128 v[194:197], v132 offset:17408
	ds_read_b128 v[198:201], v132 offset:18432
	ds_read_b128 v[202:205], v132 offset:19456
	ds_read_b128 v[206:209], v132 offset:20480
	ds_read_b128 v[210:213], v132 offset:21504
	ds_read_b128 v[214:217], v132 offset:22528
	ds_read_b128 v[218:221], v132 offset:23552
	s_waitcnt vmcnt(6)
	s_waitcnt lgkmcnt(0)
	s_barrier
	s_setprio 1
	s_waitcnt lgkmcnt(0)
	v_mfma_f32_16x16x32_bf16 v[64:67], v[146:149], v[190:193], 0
	v_mfma_f32_16x16x32_bf16 v[60:63], v[154:157], v[190:193], 0
	v_mfma_f32_16x16x32_bf16 v[48:51], v[146:149], v[198:201], 0
	v_mfma_f32_16x16x32_bf16 v[44:47], v[154:157], v[198:201], 0
	v_mfma_f32_16x16x32_bf16 v[32:35], v[146:149], v[206:209], 0
	v_mfma_f32_16x16x32_bf16 v[28:31], v[154:157], v[206:209], 0
	v_mfma_f32_16x16x32_bf16 v[16:19], v[146:149], v[214:217], 0
	v_mfma_f32_16x16x32_bf16 v[12:15], v[154:157], v[214:217], 0
	v_mfma_f32_16x16x32_bf16 v[64:67], v[150:153], v[194:197], v[64:67]
	v_mfma_f32_16x16x32_bf16 v[60:63], v[158:161], v[194:197], v[60:63]
	v_mfma_f32_16x16x32_bf16 v[48:51], v[150:153], v[202:205], v[48:51]
	v_mfma_f32_16x16x32_bf16 v[44:47], v[158:161], v[202:205], v[44:47]
	v_mfma_f32_16x16x32_bf16 v[32:35], v[150:153], v[210:213], v[32:35]
	v_mfma_f32_16x16x32_bf16 v[28:31], v[158:161], v[210:213], v[28:31]
	v_mfma_f32_16x16x32_bf16 v[16:19], v[150:153], v[218:221], v[16:19]
	v_mfma_f32_16x16x32_bf16 v[12:15], v[158:161], v[218:221], v[12:15]
	s_setprio 0
	s_setprio 1
	v_mfma_f32_16x16x32_bf16 v[56:59], v[162:165], v[190:193], 0
	v_mfma_f32_16x16x32_bf16 v[52:55], v[170:173], v[190:193], 0
	v_mfma_f32_16x16x32_bf16 v[40:43], v[162:165], v[198:201], 0
	v_mfma_f32_16x16x32_bf16 v[36:39], v[170:173], v[198:201], 0
	v_mfma_f32_16x16x32_bf16 v[24:27], v[162:165], v[206:209], 0
	v_mfma_f32_16x16x32_bf16 v[20:23], v[170:173], v[206:209], 0
	v_mfma_f32_16x16x32_bf16 v[8:11], v[162:165], v[214:217], 0
	v_mfma_f32_16x16x32_bf16 v[4:7], v[170:173], v[214:217], 0
	v_mfma_f32_16x16x32_bf16 v[56:59], v[166:169], v[194:197], v[56:59]
	v_mfma_f32_16x16x32_bf16 v[52:55], v[186:189], v[194:197], v[52:55]
	v_mfma_f32_16x16x32_bf16 v[40:43], v[166:169], v[202:205], v[40:43]
	v_mfma_f32_16x16x32_bf16 v[36:39], v[186:189], v[202:205], v[36:39]
	v_mfma_f32_16x16x32_bf16 v[24:27], v[166:169], v[210:213], v[24:27]
	v_mfma_f32_16x16x32_bf16 v[20:23], v[186:189], v[210:213], v[20:23]
	v_mfma_f32_16x16x32_bf16 v[8:11], v[166:169], v[218:221], v[8:11]
	v_mfma_f32_16x16x32_bf16 v[4:7], v[186:189], v[218:221], v[4:7]
	s_setprio 0
	s_barrier
	s_add_i32 s64, 0, 0x18000
	s_add_u32 s42, s50, 0x40000
	s_addc_u32 s43, s51, 0
	s_mov_b32 m0, s56
	s_nop 0
	global_load_lds_dwordx4 v144, s[50:51]
	s_mov_b32 m0, s57
	s_nop 0
	global_load_lds_dwordx4 v140, s[50:51]
	v_add_u32_e32 v138, s64, v3
	s_add_i32 s65, 0, 0x1c000
	ds_read_b128 v[146:149], v138
	ds_read_b128 v[150:153], v138 offset:1024
	ds_read_b128 v[154:157], v138 offset:2048
	ds_read_b128 v[158:161], v138 offset:3072
	v_add_u32_e32 v138, s65, v3
	ds_read_b128 v[162:165], v138
	ds_read_b128 v[166:169], v138 offset:1024
	ds_read_b128 v[170:173], v138 offset:2048
	ds_read_b128 v[186:189], v138 offset:3072
	s_mov_b32 m0, s58
	s_nop 0
	global_load_lds_dwordx4 v144, s[42:43]
	s_mov_b32 m0, s59
	s_nop 0
	global_load_lds_dwordx4 v140, s[42:43]
	ds_read_b128 v[190:193], v132 offset:32768
	ds_read_b128 v[194:197], v132 offset:33792
	ds_read_b128 v[198:201], v132 offset:34816
	ds_read_b128 v[202:205], v132 offset:35840
	ds_read_b128 v[206:209], v132 offset:36864
	ds_read_b128 v[210:213], v132 offset:37888
	ds_read_b128 v[214:217], v132 offset:38912
	ds_read_b128 v[218:221], v132 offset:39936
	s_waitcnt vmcnt(8)
	s_waitcnt lgkmcnt(8)
	s_barrier
	s_setprio 1
	s_waitcnt lgkmcnt(7)
	v_mfma_f32_16x16x32_bf16 v[128:131], v[146:149], v[190:193], v[128:131]
	v_mfma_f32_16x16x32_bf16 v[124:127], v[154:157], v[190:193], v[124:127]
	s_waitcnt lgkmcnt(5)
	v_mfma_f32_16x16x32_bf16 v[112:115], v[146:149], v[198:201], v[112:115]
	v_mfma_f32_16x16x32_bf16 v[108:111], v[154:157], v[198:201], v[108:111]
	s_waitcnt lgkmcnt(3)
	v_mfma_f32_16x16x32_bf16 v[96:99], v[146:149], v[206:209], v[96:99]
	v_mfma_f32_16x16x32_bf16 v[92:95], v[154:157], v[206:209], v[92:95]
	s_waitcnt lgkmcnt(1)
	v_mfma_f32_16x16x32_bf16 v[80:83], v[146:149], v[214:217], v[80:83]
	v_mfma_f32_16x16x32_bf16 v[76:79], v[154:157], v[214:217], v[76:79]
	v_mfma_f32_16x16x32_bf16 v[128:131], v[150:153], v[194:197], v[128:131]
	v_mfma_f32_16x16x32_bf16 v[124:127], v[158:161], v[194:197], v[124:127]
	v_mfma_f32_16x16x32_bf16 v[112:115], v[150:153], v[202:205], v[112:115]
	v_mfma_f32_16x16x32_bf16 v[108:111], v[158:161], v[202:205], v[108:111]
	v_mfma_f32_16x16x32_bf16 v[96:99], v[150:153], v[210:213], v[96:99]
	v_mfma_f32_16x16x32_bf16 v[92:95], v[158:161], v[210:213], v[92:95]
	s_waitcnt lgkmcnt(0)
	v_mfma_f32_16x16x32_bf16 v[80:83], v[150:153], v[218:221], v[80:83]
	v_mfma_f32_16x16x32_bf16 v[76:79], v[158:161], v[218:221], v[76:79]
	s_setprio 0
	s_setprio 1
	v_mfma_f32_16x16x32_bf16 v[120:123], v[162:165], v[190:193], v[120:123]
	v_mfma_f32_16x16x32_bf16 v[116:119], v[170:173], v[190:193], v[116:119]
	v_mfma_f32_16x16x32_bf16 v[104:107], v[162:165], v[198:201], v[104:107]
	v_mfma_f32_16x16x32_bf16 v[100:103], v[170:173], v[198:201], v[100:103]
	v_mfma_f32_16x16x32_bf16 v[88:91], v[162:165], v[206:209], v[88:91]
	v_mfma_f32_16x16x32_bf16 v[84:87], v[170:173], v[206:209], v[84:87]
	v_mfma_f32_16x16x32_bf16 v[72:75], v[162:165], v[214:217], v[72:75]
	v_mfma_f32_16x16x32_bf16 v[68:71], v[170:173], v[214:217], v[68:71]
	v_mfma_f32_16x16x32_bf16 v[120:123], v[166:169], v[194:197], v[120:123]
	v_mfma_f32_16x16x32_bf16 v[116:119], v[186:189], v[194:197], v[116:119]
	v_mfma_f32_16x16x32_bf16 v[104:107], v[166:169], v[202:205], v[104:107]
	v_mfma_f32_16x16x32_bf16 v[100:103], v[186:189], v[202:205], v[100:103]
	v_mfma_f32_16x16x32_bf16 v[88:91], v[166:169], v[210:213], v[88:91]
	v_mfma_f32_16x16x32_bf16 v[84:87], v[186:189], v[210:213], v[84:87]
	v_mfma_f32_16x16x32_bf16 v[72:75], v[166:169], v[218:221], v[72:75]
	v_mfma_f32_16x16x32_bf16 v[68:71], v[186:189], v[218:221], v[68:71]
	s_setprio 0
	s_barrier
	s_add_u32 s42, s48, 0x80
	s_addc_u32 s43, s49, 0
	s_add_i32 s50, s64, s69
	s_mov_b32 m0, s50
	s_nop 0
	global_load_lds_dwordx4 v142, s[42:43]
	s_add_i32 m0, s50, 0x2000
	s_nop 0
	global_load_lds_dwordx4 v0, s[42:43]
	s_add_u32 s42, s48, 0x40080
	s_addc_u32 s43, s49, 0
	s_add_i32 s48, s65, s69
	s_mov_b32 m0, s48
	s_nop 0
	global_load_lds_dwordx4 v142, s[42:43]
	s_add_i32 m0, s48, 0x2000
	s_nop 0
	global_load_lds_dwordx4 v0, s[42:43]
	ds_read_b128 v[190:193], v132 offset:49152
	ds_read_b128 v[194:197], v132 offset:50176
	ds_read_b128 v[198:201], v132 offset:51200
	ds_read_b128 v[202:205], v132 offset:52224
	ds_read_b128 v[206:209], v132 offset:53248
	ds_read_b128 v[210:213], v132 offset:54272
	ds_read_b128 v[214:217], v132 offset:55296
	ds_read_b128 v[218:221], v132 offset:56320
	s_waitcnt vmcnt(6)
	s_waitcnt lgkmcnt(0)
	s_barrier
	s_setprio 1
	s_waitcnt lgkmcnt(0)
	v_mfma_f32_16x16x32_bf16 v[64:67], v[146:149], v[190:193], v[64:67]
	v_mfma_f32_16x16x32_bf16 v[60:63], v[154:157], v[190:193], v[60:63]
	v_mfma_f32_16x16x32_bf16 v[48:51], v[146:149], v[198:201], v[48:51]
	v_mfma_f32_16x16x32_bf16 v[44:47], v[154:157], v[198:201], v[44:47]
	v_mfma_f32_16x16x32_bf16 v[32:35], v[146:149], v[206:209], v[32:35]
	v_mfma_f32_16x16x32_bf16 v[28:31], v[154:157], v[206:209], v[28:31]
	v_mfma_f32_16x16x32_bf16 v[16:19], v[146:149], v[214:217], v[16:19]
	v_mfma_f32_16x16x32_bf16 v[12:15], v[154:157], v[214:217], v[12:15]
	v_mfma_f32_16x16x32_bf16 v[64:67], v[150:153], v[194:197], v[64:67]
	v_mfma_f32_16x16x32_bf16 v[60:63], v[158:161], v[194:197], v[60:63]
	v_mfma_f32_16x16x32_bf16 v[48:51], v[150:153], v[202:205], v[48:51]
	v_mfma_f32_16x16x32_bf16 v[44:47], v[158:161], v[202:205], v[44:47]
	v_mfma_f32_16x16x32_bf16 v[32:35], v[150:153], v[210:213], v[32:35]
	v_mfma_f32_16x16x32_bf16 v[28:31], v[158:161], v[210:213], v[28:31]
	v_mfma_f32_16x16x32_bf16 v[16:19], v[150:153], v[218:221], v[16:19]
	v_mfma_f32_16x16x32_bf16 v[12:15], v[158:161], v[218:221], v[12:15]
	s_setprio 0
	s_setprio 1
	v_mfma_f32_16x16x32_bf16 v[56:59], v[162:165], v[190:193], v[56:59]
	v_mfma_f32_16x16x32_bf16 v[52:55], v[170:173], v[190:193], v[52:55]
	v_mfma_f32_16x16x32_bf16 v[40:43], v[162:165], v[198:201], v[40:43]
	v_mfma_f32_16x16x32_bf16 v[36:39], v[170:173], v[198:201], v[36:39]
	v_mfma_f32_16x16x32_bf16 v[24:27], v[162:165], v[206:209], v[24:27]
	v_mfma_f32_16x16x32_bf16 v[20:23], v[170:173], v[206:209], v[20:23]
	v_mfma_f32_16x16x32_bf16 v[8:11], v[162:165], v[214:217], v[8:11]
	v_mfma_f32_16x16x32_bf16 v[4:7], v[170:173], v[214:217], v[4:7]
	v_mfma_f32_16x16x32_bf16 v[56:59], v[166:169], v[194:197], v[56:59]
	v_mfma_f32_16x16x32_bf16 v[52:55], v[186:189], v[194:197], v[52:55]
	v_mfma_f32_16x16x32_bf16 v[40:43], v[166:169], v[202:205], v[40:43]
	v_mfma_f32_16x16x32_bf16 v[36:39], v[186:189], v[202:205], v[36:39]
	v_mfma_f32_16x16x32_bf16 v[24:27], v[166:169], v[210:213], v[24:27]
	v_mfma_f32_16x16x32_bf16 v[20:23], v[186:189], v[210:213], v[20:23]
	v_mfma_f32_16x16x32_bf16 v[8:11], v[166:169], v[218:221], v[8:11]
	v_mfma_f32_16x16x32_bf16 v[4:7], v[186:189], v[218:221], v[4:7]
	s_setprio 0
	s_barrier
	s_add_i32 s63, s63, 2
	s_add_u32 s28, s28, 0x100
	s_addc_u32 s29, s29, 0
	s_cmp_gt_u32 s63, 13
	s_mov_b64 s[42:43], s[44:45]

.LBB0_500:
	s_add_u32 s44, s42, 0x100
	s_addc_u32 s45, s43, 0
	s_cmp_eq_u32 s63, 12
	s_cselect_b32 s50, s26, s44
	s_cselect_b32 s51, s5, s45
	s_cselect_b32 s48, s27, s28
	s_cselect_b32 s49, s23, s29
	s_add_i32 s64, 0, 0x10000
	s_add_u32 s46, s42, 0x80
	s_addc_u32 s47, s43, 0
	s_add_u32 s42, s42, 0x40080
	s_addc_u32 s43, s43, 0
	s_mov_b32 m0, s60
	s_nop 0
	global_load_lds_dwordx4 v144, s[46:47]
	s_mov_b32 m0, s61
	s_nop 0
	global_load_lds_dwordx4 v140, s[46:47]
	v_add_u32_e32 v138, s64, v3
	s_add_i32 s65, 0, 0x14000
	ds_read_b128 v[146:149], v138
	ds_read_b128 v[150:153], v138 offset:1024
	ds_read_b128 v[154:157], v138 offset:2048
	ds_read_b128 v[158:161], v138 offset:3072
	v_add_u32_e32 v138, s65, v3
	ds_read_b128 v[162:165], v138
	ds_read_b128 v[166:169], v138 offset:1024
	ds_read_b128 v[170:173], v138 offset:2048
	ds_read_b128 v[186:189], v138 offset:3072
	s_add_i32 m0, s56, 0xc000
	s_nop 0
	global_load_lds_dwordx4 v144, s[42:43]
	s_add_i32 m0, s56, 0xe000
	s_nop 0
	global_load_lds_dwordx4 v140, s[42:43]
	ds_read_b128 v[190:193], v132
	ds_read_b128 v[194:197], v132 offset:1024
	ds_read_b128 v[198:201], v132 offset:2048
	ds_read_b128 v[202:205], v132 offset:3072
	ds_read_b128 v[206:209], v132 offset:4096
	ds_read_b128 v[210:213], v132 offset:5120
	ds_read_b128 v[214:217], v132 offset:6144
	ds_read_b128 v[218:221], v132 offset:7168
	s_waitcnt vmcnt(8)
	s_waitcnt lgkmcnt(8)
	s_barrier
	s_setprio 1
	s_waitcnt lgkmcnt(7)
	v_mfma_f32_16x16x32_bf16 v[128:131], v[146:149], v[190:193], v[128:131]
	v_mfma_f32_16x16x32_bf16 v[124:127], v[154:157], v[190:193], v[124:127]
	s_waitcnt lgkmcnt(5)
	v_mfma_f32_16x16x32_bf16 v[112:115], v[146:149], v[198:201], v[112:115]
	v_mfma_f32_16x16x32_bf16 v[108:111], v[154:157], v[198:201], v[108:111]
	s_waitcnt lgkmcnt(3)
	v_mfma_f32_16x16x32_bf16 v[96:99], v[146:149], v[206:209], v[96:99]
	v_mfma_f32_16x16x32_bf16 v[92:95], v[154:157], v[206:209], v[92:95]
	s_waitcnt lgkmcnt(1)
	v_mfma_f32_16x16x32_bf16 v[80:83], v[146:149], v[214:217], v[80:83]
	v_mfma_f32_16x16x32_bf16 v[76:79], v[154:157], v[214:217], v[76:79]
	v_mfma_f32_16x16x32_bf16 v[128:131], v[150:153], v[194:197], v[128:131]
	v_mfma_f32_16x16x32_bf16 v[124:127], v[158:161], v[194:197], v[124:127]
	v_mfma_f32_16x16x32_bf16 v[112:115], v[150:153], v[202:205], v[112:115]
	v_mfma_f32_16x16x32_bf16 v[108:111], v[158:161], v[202:205], v[108:111]
	v_mfma_f32_16x16x32_bf16 v[96:99], v[150:153], v[210:213], v[96:99]
	v_mfma_f32_16x16x32_bf16 v[92:95], v[158:161], v[210:213], v[92:95]
	s_waitcnt lgkmcnt(0)
	v_mfma_f32_16x16x32_bf16 v[80:83], v[150:153], v[218:221], v[80:83]
	v_mfma_f32_16x16x32_bf16 v[76:79], v[158:161], v[218:221], v[76:79]
	s_setprio 0
	s_setprio 1
	v_mfma_f32_16x16x32_bf16 v[120:123], v[162:165], v[190:193], v[120:123]
	v_mfma_f32_16x16x32_bf16 v[116:119], v[170:173], v[190:193], v[116:119]
	v_mfma_f32_16x16x32_bf16 v[104:107], v[162:165], v[198:201], v[104:107]
	v_mfma_f32_16x16x32_bf16 v[100:103], v[170:173], v[198:201], v[100:103]
	v_mfma_f32_16x16x32_bf16 v[88:91], v[162:165], v[206:209], v[88:91]
	v_mfma_f32_16x16x32_bf16 v[84:87], v[170:173], v[206:209], v[84:87]
	v_mfma_f32_16x16x32_bf16 v[72:75], v[162:165], v[214:217], v[72:75]
	v_mfma_f32_16x16x32_bf16 v[68:71], v[170:173], v[214:217], v[68:71]
	v_mfma_f32_16x16x32_bf16 v[120:123], v[166:169], v[194:197], v[120:123]
	v_mfma_f32_16x16x32_bf16 v[116:119], v[186:189], v[194:197], v[116:119]
	v_mfma_f32_16x16x32_bf16 v[104:107], v[166:169], v[202:205], v[104:107]
	v_mfma_f32_16x16x32_bf16 v[100:103], v[186:189], v[202:205], v[100:103]
	v_mfma_f32_16x16x32_bf16 v[88:91], v[166:169], v[210:213], v[88:91]
	v_mfma_f32_16x16x32_bf16 v[84:87], v[186:189], v[210:213], v[84:87]
	v_mfma_f32_16x16x32_bf16 v[72:75], v[166:169], v[218:221], v[72:75]
	v_mfma_f32_16x16x32_bf16 v[68:71], v[186:189], v[218:221], v[68:71]
	s_setprio 0
	s_barrier
	s_add_i32 s42, s64, s69
	s_mov_b32 m0, s42
	s_nop 0
	global_load_lds_dwordx4 v142, s[48:49]
	s_add_i32 m0, s42, 0x2000
	s_add_u32 s42, s48, 0x40000
	s_addc_u32 s43, s49, 0
	s_add_i32 s64, s65, s69
	global_load_lds_dwordx4 v0, s[48:49]
	s_mov_b32 m0, s64
	s_nop 0
	global_load_lds_dwordx4 v142, s[42:43]
	s_add_i32 m0, s64, 0x2000
	s_nop 0
	global_load_lds_dwordx4 v0, s[42:43]
	ds_read_b128 v[190:193], v132 offset:16384
	ds_read_b128 v[194:197], v132 offset:17408
	ds_read_b128 v[198:201], v132 offset:18432
	ds_read_b128 v[202:205], v132 offset:19456
	ds_read_b128 v[206:209], v132 offset:20480
	ds_read_b128 v[210:213], v132 offset:21504
	ds_read_b128 v[214:217], v132 offset:22528
	ds_read_b128 v[218:221], v132 offset:23552
	s_waitcnt vmcnt(6)
	s_waitcnt lgkmcnt(0)
	s_barrier
	s_setprio 1
	s_waitcnt lgkmcnt(0)
	v_mfma_f32_16x16x32_bf16 v[64:67], v[146:149], v[190:193], v[64:67]
	v_mfma_f32_16x16x32_bf16 v[60:63], v[154:157], v[190:193], v[60:63]
	v_mfma_f32_16x16x32_bf16 v[48:51], v[146:149], v[198:201], v[48:51]
	v_mfma_f32_16x16x32_bf16 v[44:47], v[154:157], v[198:201], v[44:47]
	v_mfma_f32_16x16x32_bf16 v[32:35], v[146:149], v[206:209], v[32:35]
	v_mfma_f32_16x16x32_bf16 v[28:31], v[154:157], v[206:209], v[28:31]
	v_mfma_f32_16x16x32_bf16 v[16:19], v[146:149], v[214:217], v[16:19]
	v_mfma_f32_16x16x32_bf16 v[12:15], v[154:157], v[214:217], v[12:15]
	v_mfma_f32_16x16x32_bf16 v[64:67], v[150:153], v[194:197], v[64:67]
	v_mfma_f32_16x16x32_bf16 v[60:63], v[158:161], v[194:197], v[60:63]
	v_mfma_f32_16x16x32_bf16 v[48:51], v[150:153], v[202:205], v[48:51]
	v_mfma_f32_16x16x32_bf16 v[44:47], v[158:161], v[202:205], v[44:47]
	v_mfma_f32_16x16x32_bf16 v[32:35], v[150:153], v[210:213], v[32:35]
	v_mfma_f32_16x16x32_bf16 v[28:31], v[158:161], v[210:213], v[28:31]
	v_mfma_f32_16x16x32_bf16 v[16:19], v[150:153], v[218:221], v[16:19]
	v_mfma_f32_16x16x32_bf16 v[12:15], v[158:161], v[218:221], v[12:15]
	s_setprio 0
	s_setprio 1
	v_mfma_f32_16x16x32_bf16 v[56:59], v[162:165], v[190:193], v[56:59]
	v_mfma_f32_16x16x32_bf16 v[52:55], v[170:173], v[190:193], v[52:55]
	v_mfma_f32_16x16x32_bf16 v[40:43], v[162:165], v[198:201], v[40:43]
	v_mfma_f32_16x16x32_bf16 v[36:39], v[170:173], v[198:201], v[36:39]
	v_mfma_f32_16x16x32_bf16 v[24:27], v[162:165], v[206:209], v[24:27]
	v_mfma_f32_16x16x32_bf16 v[20:23], v[170:173], v[206:209], v[20:23]
	v_mfma_f32_16x16x32_bf16 v[8:11], v[162:165], v[214:217], v[8:11]
	v_mfma_f32_16x16x32_bf16 v[4:7], v[170:173], v[214:217], v[4:7]
	v_mfma_f32_16x16x32_bf16 v[56:59], v[166:169], v[194:197], v[56:59]
	v_mfma_f32_16x16x32_bf16 v[52:55], v[186:189], v[194:197], v[52:55]
	v_mfma_f32_16x16x32_bf16 v[40:43], v[166:169], v[202:205], v[40:43]
	v_mfma_f32_16x16x32_bf16 v[36:39], v[186:189], v[202:205], v[36:39]
	v_mfma_f32_16x16x32_bf16 v[24:27], v[166:169], v[210:213], v[24:27]
	v_mfma_f32_16x16x32_bf16 v[20:23], v[186:189], v[210:213], v[20:23]
	v_mfma_f32_16x16x32_bf16 v[8:11], v[166:169], v[218:221], v[8:11]
	v_mfma_f32_16x16x32_bf16 v[4:7], v[186:189], v[218:221], v[4:7]
	s_setprio 0
	s_barrier
	s_add_i32 s64, 0, 0x18000
	s_add_u32 s42, s50, 0x40000
	s_addc_u32 s43, s51, 0
	s_mov_b32 m0, s56
	s_nop 0
	global_load_lds_dwordx4 v144, s[50:51]
	s_mov_b32 m0, s57
	s_nop 0
	global_load_lds_dwordx4 v140, s[50:51]
	v_add_u32_e32 v138, s64, v3
	s_add_i32 s65, 0, 0x1c000
	ds_read_b128 v[146:149], v138
	ds_read_b128 v[150:153], v138 offset:1024
	ds_read_b128 v[154:157], v138 offset:2048
	ds_read_b128 v[158:161], v138 offset:3072
	v_add_u32_e32 v138, s65, v3
	ds_read_b128 v[162:165], v138
	ds_read_b128 v[166:169], v138 offset:1024
	ds_read_b128 v[170:173], v138 offset:2048
	ds_read_b128 v[186:189], v138 offset:3072
	s_mov_b32 m0, s58
	s_nop 0
	global_load_lds_dwordx4 v144, s[42:43]
	s_mov_b32 m0, s59
	s_nop 0
	global_load_lds_dwordx4 v140, s[42:43]
	ds_read_b128 v[190:193], v132 offset:32768
	ds_read_b128 v[194:197], v132 offset:33792
	ds_read_b128 v[198:201], v132 offset:34816
	ds_read_b128 v[202:205], v132 offset:35840
	ds_read_b128 v[206:209], v132 offset:36864
	ds_read_b128 v[210:213], v132 offset:37888
	ds_read_b128 v[214:217], v132 offset:38912
	ds_read_b128 v[218:221], v132 offset:39936
	s_waitcnt vmcnt(8)
	s_waitcnt lgkmcnt(8)
	s_barrier
	s_setprio 1
	s_waitcnt lgkmcnt(7)
	v_mfma_f32_16x16x32_bf16 v[128:131], v[146:149], v[190:193], v[128:131]
	v_mfma_f32_16x16x32_bf16 v[124:127], v[154:157], v[190:193], v[124:127]
	s_waitcnt lgkmcnt(5)
	v_mfma_f32_16x16x32_bf16 v[112:115], v[146:149], v[198:201], v[112:115]
	v_mfma_f32_16x16x32_bf16 v[108:111], v[154:157], v[198:201], v[108:111]
	s_waitcnt lgkmcnt(3)
	v_mfma_f32_16x16x32_bf16 v[96:99], v[146:149], v[206:209], v[96:99]
	v_mfma_f32_16x16x32_bf16 v[92:95], v[154:157], v[206:209], v[92:95]
	s_waitcnt lgkmcnt(1)
	v_mfma_f32_16x16x32_bf16 v[80:83], v[146:149], v[214:217], v[80:83]
	v_mfma_f32_16x16x32_bf16 v[76:79], v[154:157], v[214:217], v[76:79]
	v_mfma_f32_16x16x32_bf16 v[128:131], v[150:153], v[194:197], v[128:131]
	v_mfma_f32_16x16x32_bf16 v[124:127], v[158:161], v[194:197], v[124:127]
	v_mfma_f32_16x16x32_bf16 v[112:115], v[150:153], v[202:205], v[112:115]
	v_mfma_f32_16x16x32_bf16 v[108:111], v[158:161], v[202:205], v[108:111]
	v_mfma_f32_16x16x32_bf16 v[96:99], v[150:153], v[210:213], v[96:99]
	v_mfma_f32_16x16x32_bf16 v[92:95], v[158:161], v[210:213], v[92:95]
	s_waitcnt lgkmcnt(0)
	v_mfma_f32_16x16x32_bf16 v[80:83], v[150:153], v[218:221], v[80:83]
	v_mfma_f32_16x16x32_bf16 v[76:79], v[158:161], v[218:221], v[76:79]
	s_setprio 0
	s_setprio 1
	v_mfma_f32_16x16x32_bf16 v[120:123], v[162:165], v[190:193], v[120:123]
	v_mfma_f32_16x16x32_bf16 v[116:119], v[170:173], v[190:193], v[116:119]
	v_mfma_f32_16x16x32_bf16 v[104:107], v[162:165], v[198:201], v[104:107]
	v_mfma_f32_16x16x32_bf16 v[100:103], v[170:173], v[198:201], v[100:103]
	v_mfma_f32_16x16x32_bf16 v[88:91], v[162:165], v[206:209], v[88:91]
	v_mfma_f32_16x16x32_bf16 v[84:87], v[170:173], v[206:209], v[84:87]
	v_mfma_f32_16x16x32_bf16 v[72:75], v[162:165], v[214:217], v[72:75]
	v_mfma_f32_16x16x32_bf16 v[68:71], v[170:173], v[214:217], v[68:71]
	v_mfma_f32_16x16x32_bf16 v[120:123], v[166:169], v[194:197], v[120:123]
	v_mfma_f32_16x16x32_bf16 v[116:119], v[186:189], v[194:197], v[116:119]
	v_mfma_f32_16x16x32_bf16 v[104:107], v[166:169], v[202:205], v[104:107]
	v_mfma_f32_16x16x32_bf16 v[100:103], v[186:189], v[202:205], v[100:103]
	v_mfma_f32_16x16x32_bf16 v[88:91], v[166:169], v[210:213], v[88:91]
	v_mfma_f32_16x16x32_bf16 v[84:87], v[186:189], v[210:213], v[84:87]
	v_mfma_f32_16x16x32_bf16 v[72:75], v[166:169], v[218:221], v[72:75]
	v_mfma_f32_16x16x32_bf16 v[68:71], v[186:189], v[218:221], v[68:71]
	s_setprio 0
	s_barrier
	s_add_u32 s42, s48, 0x80
	s_addc_u32 s43, s49, 0
	s_add_i32 s50, s64, s69
	s_mov_b32 m0, s50
	s_nop 0
	global_load_lds_dwordx4 v142, s[42:43]
	s_add_i32 m0, s50, 0x2000
	s_nop 0
	global_load_lds_dwordx4 v0, s[42:43]
	s_add_u32 s42, s48, 0x40080
	s_addc_u32 s43, s49, 0
	s_add_i32 s48, s65, s69
	s_mov_b32 m0, s48
	s_nop 0
	global_load_lds_dwordx4 v142, s[42:43]
	s_add_i32 m0, s48, 0x2000
	s_nop 0
	global_load_lds_dwordx4 v0, s[42:43]
	ds_read_b128 v[190:193], v132 offset:49152
	ds_read_b128 v[194:197], v132 offset:50176
	ds_read_b128 v[198:201], v132 offset:51200
	ds_read_b128 v[202:205], v132 offset:52224
	ds_read_b128 v[206:209], v132 offset:53248
	ds_read_b128 v[210:213], v132 offset:54272
	ds_read_b128 v[214:217], v132 offset:55296
	ds_read_b128 v[218:221], v132 offset:56320
	s_waitcnt vmcnt(6)
	s_waitcnt lgkmcnt(0)
	s_barrier
	s_setprio 1
	s_waitcnt lgkmcnt(0)
	v_mfma_f32_16x16x32_bf16 v[64:67], v[146:149], v[190:193], v[64:67]
	v_mfma_f32_16x16x32_bf16 v[60:63], v[154:157], v[190:193], v[60:63]
	v_mfma_f32_16x16x32_bf16 v[48:51], v[146:149], v[198:201], v[48:51]
	v_mfma_f32_16x16x32_bf16 v[44:47], v[154:157], v[198:201], v[44:47]
	v_mfma_f32_16x16x32_bf16 v[32:35], v[146:149], v[206:209], v[32:35]
	v_mfma_f32_16x16x32_bf16 v[28:31], v[154:157], v[206:209], v[28:31]
	v_mfma_f32_16x16x32_bf16 v[16:19], v[146:149], v[214:217], v[16:19]
	v_mfma_f32_16x16x32_bf16 v[12:15], v[154:157], v[214:217], v[12:15]
	v_mfma_f32_16x16x32_bf16 v[64:67], v[150:153], v[194:197], v[64:67]
	v_mfma_f32_16x16x32_bf16 v[60:63], v[158:161], v[194:197], v[60:63]
	v_mfma_f32_16x16x32_bf16 v[48:51], v[150:153], v[202:205], v[48:51]
	v_mfma_f32_16x16x32_bf16 v[44:47], v[158:161], v[202:205], v[44:47]
	v_mfma_f32_16x16x32_bf16 v[32:35], v[150:153], v[210:213], v[32:35]
	v_mfma_f32_16x16x32_bf16 v[28:31], v[158:161], v[210:213], v[28:31]
	v_mfma_f32_16x16x32_bf16 v[16:19], v[150:153], v[218:221], v[16:19]
	v_mfma_f32_16x16x32_bf16 v[12:15], v[158:161], v[218:221], v[12:15]
	s_setprio 0
	s_setprio 1
	v_mfma_f32_16x16x32_bf16 v[56:59], v[162:165], v[190:193], v[56:59]
	v_mfma_f32_16x16x32_bf16 v[52:55], v[170:173], v[190:193], v[52:55]
	v_mfma_f32_16x16x32_bf16 v[40:43], v[162:165], v[198:201], v[40:43]
	v_mfma_f32_16x16x32_bf16 v[36:39], v[170:173], v[198:201], v[36:39]
	v_mfma_f32_16x16x32_bf16 v[24:27], v[162:165], v[206:209], v[24:27]
	v_mfma_f32_16x16x32_bf16 v[20:23], v[170:173], v[206:209], v[20:23]
	v_mfma_f32_16x16x32_bf16 v[8:11], v[162:165], v[214:217], v[8:11]
	v_mfma_f32_16x16x32_bf16 v[4:7], v[170:173], v[214:217], v[4:7]
	v_mfma_f32_16x16x32_bf16 v[56:59], v[166:169], v[194:197], v[56:59]
	v_mfma_f32_16x16x32_bf16 v[52:55], v[186:189], v[194:197], v[52:55]
	v_mfma_f32_16x16x32_bf16 v[40:43], v[166:169], v[202:205], v[40:43]
	v_mfma_f32_16x16x32_bf16 v[36:39], v[186:189], v[202:205], v[36:39]
	v_mfma_f32_16x16x32_bf16 v[24:27], v[166:169], v[210:213], v[24:27]
	v_mfma_f32_16x16x32_bf16 v[20:23], v[186:189], v[210:213], v[20:23]
	v_mfma_f32_16x16x32_bf16 v[8:11], v[166:169], v[218:221], v[8:11]
	v_mfma_f32_16x16x32_bf16 v[4:7], v[186:189], v[218:221], v[4:7]
	s_setprio 0
	s_barrier
	s_add_i32 s63, s63, 2
	s_add_u32 s28, s28, 0x100
	s_addc_u32 s29, s29, 0
	s_cmp_gt_u32 s63, 13
	s_mov_b64 s[42:43], s[44:45]
	s_cbranch_scc0 .LBB0_500
	s_and_b64 vcc, exec, s[14:15]
	s_cbranch_vccz .LBB0_503
	s_barrier
